# grid barrier: acquire L1 invalidate issued before the spin (off the critical path) instead of after the release
# speedup vs baseline: 1.0118x; 1.0118x over previous
; __device__ __forceinline__ unsigned xb_ld(unsigned* p)              { return __hip_atomic_load(p, __ATOMIC_RELAXED, __HIP_MEMORY_SCOPE_AGENT); }
; __device__ __forceinline__ unsigned xb_add(unsigned* p, unsigned v) { return __hip_atomic_fetch_add(p, v, __ATOMIC_RELAXED, __HIP_MEMORY_SCOPE_AGENT); }
; #define XB_SPIN(cond, bar) do { unsigned _sp = 0; while (cond) { __builtin_amdgcn_s_sleep(1); \
;     if ((++_sp & 255u) == 0u) { if (xb_ld(&(bar)[XB_TMO])) break; if (_sp > XB_SPIN_CAP) { atomicAdd(&(bar)[XB_TMO], 1u); break; } } } } while (0)
; __device__ __forceinline__ void xcd_barrier(const XcdBarrier& b) {
;     ...
;         const unsigned old = xb_add(&bar[XB_XSUB(b.x)], 1u);
;         const unsigned gen = old / nloc;
;         if (old + 1u == (gen + 1u) * nloc) {
;             __builtin_amdgcn_fence(__ATOMIC_RELEASE, "agent");
;             asm volatile("s_waitcnt vmcnt(0)" ::: "memory");
;             const unsigned og = xb_add(&bar[XB_TOP], 1u);
;             const unsigned tg = og / nx;
;             if (og + 1u == (tg + 1u) * nx) xb_add(&bar[XB_TOPGEN], 1u);
;             else XB_SPIN(xb_ld(&bar[XB_TOPGEN]) == tg, bar);
;             __builtin_amdgcn_fence(__ATOMIC_ACQUIRE, "agent");
;             xb_add(&bar[XB_XGEN(b.x)], 1u);
;             asm volatile("s_waitcnt vmcnt(0)" ::: "memory");
;         } else {
;             XB_SPIN(xb_ld(&bar[XB_XGEN(b.x)]) == gen, bar);
.LBB0_58:
	s_or_b64 exec, exec, s[28:29]
	v_cvt_f32_u32_e32 v4, v2
	s_waitcnt vmcnt(0)
	v_readfirstlane_b32 s6, v3
	v_sub_u32_e32 v3, 0, v2
	v_rcp_iflag_f32_e32 v4, v4
	v_add_u32_e32 v5, s6, v1
	v_mul_f32_e32 v4, 0x4f7ffffe, v4
	v_cvt_u32_f32_e32 v4, v4
	v_mul_lo_u32 v1, v3, v4
	v_mul_hi_u32 v1, v4, v1
	v_add_u32_e32 v1, v4, v1
	v_mul_hi_u32 v1, v5, v1
	v_mul_lo_u32 v3, v1, v2
	v_sub_u32_e32 v3, v5, v3
	v_add_u32_e32 v4, 1, v1
	v_cmp_ge_u32_e32 vcc, v3, v2
	s_nop 1
	v_cndmask_b32_e32 v1, v1, v4, vcc
	v_sub_u32_e32 v4, v3, v2
	v_cndmask_b32_e32 v3, v3, v4, vcc
	v_add_u32_e32 v4, 1, v1
	v_cmp_ge_u32_e32 vcc, v3, v2
	v_add_u32_e32 v3, 1, v5
	s_nop 0
	v_cndmask_b32_e32 v1, v1, v4, vcc
	v_mul_lo_u32 v4, v2, v1
	v_add_u32_e32 v2, v4, v2
	v_cmp_ne_u32_e32 vcc, v3, v2
	s_and_saveexec_b64 s[6:7], vcc
	s_xor_b64 s[6:7], exec, s[6:7]
	s_cbranch_execz .LBB0_72
	s_waitcnt lgkmcnt(0)
	buffer_inv sc1
	v_mov_b32_e32 v0, 0x2000
	global_load_dword v0, v0, s[30:31] offset:1024 sc1
	s_add_u32 s38, s30, 0x2400
	s_addc_u32 s39, s31, 0
	s_waitcnt vmcnt(0)
	v_cmp_eq_u32_e32 vcc, v0, v1
	s_and_saveexec_b64 s[34:35], vcc
	s_cbranch_execz .LBB0_71
	s_add_u32 s36, s72, 0x80200
	s_addc_u32 s37, s73, 0
	s_mov_b32 s8, 1
	s_mov_b64 s[50:51], 0
	v_mov_b32_e32 v0, 0
	s_branch .LBB0_62

; __device__ __forceinline__ unsigned xb_ld(unsigned* p)              { return __hip_atomic_load(p, __ATOMIC_RELAXED, __HIP_MEMORY_SCOPE_AGENT); }
; __device__ __forceinline__ unsigned xb_add(unsigned* p, unsigned v) { return __hip_atomic_fetch_add(p, v, __ATOMIC_RELAXED, __HIP_MEMORY_SCOPE_AGENT); }
; #define XB_SPIN(cond, bar) do { unsigned _sp = 0; while (cond) { __builtin_amdgcn_s_sleep(1); \
;     if ((++_sp & 255u) == 0u) { if (xb_ld(&(bar)[XB_TMO])) break; if (_sp > XB_SPIN_CAP) { atomicAdd(&(bar)[XB_TMO], 1u); break; } } } } while (0)
; __device__ __forceinline__ void xcd_barrier(const XcdBarrier& b) {
;     ...
;             __builtin_amdgcn_fence(__ATOMIC_RELEASE, "agent");
;             asm volatile("s_waitcnt vmcnt(0)" ::: "memory");
;             const unsigned og = xb_add(&bar[XB_TOP], 1u);
;             const unsigned tg = og / nx;
;             if (og + 1u == (tg + 1u) * nx) xb_add(&bar[XB_TOPGEN], 1u);
;             else XB_SPIN(xb_ld(&bar[XB_TOPGEN]) == tg, bar);
;             __builtin_amdgcn_fence(__ATOMIC_ACQUIRE, "agent");
;             xb_add(&bar[XB_XGEN(b.x)], 1u);
;             asm volatile("s_waitcnt vmcnt(0)" ::: "memory");
;         } else {
;             XB_SPIN(xb_ld(&bar[XB_XGEN(b.x)]) == gen, bar);
;             __builtin_amdgcn_fence(__ATOMIC_ACQUIRE, "agent");
;             asm volatile("s_waitcnt vmcnt(0)" ::: "memory");
.LBB0_71:
	s_or_b64 exec, exec, s[34:35]
	s_waitcnt vmcnt(0)
	s_nop 0
	s_waitcnt vmcnt(0)
.LBB0_72:
	s_andn2_saveexec_b64 s[6:7], s[6:7]
	s_cbranch_execz .LBB0_92
	s_mov_b64 s[6:7], exec
	buffer_inv sc1
	buffer_wbl2 sc1
	s_waitcnt lgkmcnt(0)
	s_waitcnt vmcnt(0)
	v_mbcnt_lo_u32_b32 v1, s6, 0
	v_mbcnt_hi_u32_b32 v1, s7, v1
	v_cmp_eq_u32_e32 vcc, 0, v1
	s_and_saveexec_b64 s[28:29], vcc
	s_cbranch_execz .LBB0_75
	s_bcnt1_i32_b64 s6, s[6:7]
	v_mov_b32_e32 v2, 0x83000
	v_mov_b32_e32 v3, s6
	global_atomic_add v2, v2, v3, s[72:73] offset:1024 sc0

; __device__ __forceinline__ unsigned xb_ld(unsigned* p)              { return __hip_atomic_load(p, __ATOMIC_RELAXED, __HIP_MEMORY_SCOPE_AGENT); }
; __device__ __forceinline__ unsigned xb_add(unsigned* p, unsigned v) { return __hip_atomic_fetch_add(p, v, __ATOMIC_RELAXED, __HIP_MEMORY_SCOPE_AGENT); }
; #define XB_SPIN(cond, bar) do { unsigned _sp = 0; while (cond) { __builtin_amdgcn_s_sleep(1); \
;     if ((++_sp & 255u) == 0u) { if (xb_ld(&(bar)[XB_TMO])) break; if (_sp > XB_SPIN_CAP) { atomicAdd(&(bar)[XB_TMO], 1u); break; } } } } while (0)
; __device__ __forceinline__ void xcd_barrier(const XcdBarrier& b) {
;     ...
;             if (og + 1u == (tg + 1u) * nx) xb_add(&bar[XB_TOPGEN], 1u);
;             else XB_SPIN(xb_ld(&bar[XB_TOPGEN]) == tg, bar);
;             __builtin_amdgcn_fence(__ATOMIC_ACQUIRE, "agent");
;             xb_add(&bar[XB_XGEN(b.x)], 1u);
;             asm volatile("s_waitcnt vmcnt(0)" ::: "memory");
.LBB0_89:
	s_or_b64 exec, exec, s[6:7]
	s_mov_b64 s[6:7], exec
	v_mbcnt_lo_u32_b32 v0, s6, 0
	v_mbcnt_hi_u32_b32 v0, s7, v0
	v_cmp_eq_u32_e32 vcc, 0, v0
	s_waitcnt vmcnt(0)
	s_nop 0
	s_and_saveexec_b64 s[28:29], vcc
	s_cbranch_execz .LBB0_91
	s_bcnt1_i32_b64 s6, s[6:7]
	v_mov_b32_e32 v0, 0x2000
	v_mov_b32_e32 v1, s6
	global_atomic_add v0, v1, s[30:31] offset:1024

; __device__ __forceinline__ unsigned xb_ld(unsigned* p)              { return __hip_atomic_load(p, __ATOMIC_RELAXED, __HIP_MEMORY_SCOPE_AGENT); }
; __device__ __forceinline__ unsigned xb_add(unsigned* p, unsigned v) { return __hip_atomic_fetch_add(p, v, __ATOMIC_RELAXED, __HIP_MEMORY_SCOPE_AGENT); }
; #define XB_SPIN(cond, bar) do { unsigned _sp = 0; while (cond) { __builtin_amdgcn_s_sleep(1); \
;     if ((++_sp & 255u) == 0u) { if (xb_ld(&(bar)[XB_TMO])) break; if (_sp > XB_SPIN_CAP) { atomicAdd(&(bar)[XB_TMO], 1u); break; } } } } while (0)
; __device__ __forceinline__ void xcd_barrier(const XcdBarrier& b) {
;     ...
;         const unsigned old = xb_add(&bar[XB_XSUB(b.x)], 1u);
;         const unsigned gen = old / nloc;
;         if (old + 1u == (gen + 1u) * nloc) {
;             __builtin_amdgcn_fence(__ATOMIC_RELEASE, "agent");
;             asm volatile("s_waitcnt vmcnt(0)" ::: "memory");
;             const unsigned og = xb_add(&bar[XB_TOP], 1u);
;             const unsigned tg = og / nx;
;             if (og + 1u == (tg + 1u) * nx) xb_add(&bar[XB_TOPGEN], 1u);
;             else XB_SPIN(xb_ld(&bar[XB_TOPGEN]) == tg, bar);
;             __builtin_amdgcn_fence(__ATOMIC_ACQUIRE, "agent");
;             xb_add(&bar[XB_XGEN(b.x)], 1u);
;             asm volatile("s_waitcnt vmcnt(0)" ::: "memory");
;         } else {
;             XB_SPIN(xb_ld(&bar[XB_XGEN(b.x)]) == gen, bar);
.LBB0_197:
	s_or_b64 exec, exec, s[28:29]
	v_cvt_f32_u32_e32 v4, v2
	s_waitcnt vmcnt(0)
	v_readfirstlane_b32 s6, v3
	v_sub_u32_e32 v3, 0, v2
	v_rcp_iflag_f32_e32 v4, v4
	v_add_u32_e32 v5, s6, v1
	v_mul_f32_e32 v4, 0x4f7ffffe, v4
	v_cvt_u32_f32_e32 v4, v4
	v_mul_lo_u32 v1, v3, v4
	v_mul_hi_u32 v1, v4, v1
	v_add_u32_e32 v1, v4, v1
	v_mul_hi_u32 v1, v5, v1
	v_mul_lo_u32 v3, v1, v2
	v_sub_u32_e32 v3, v5, v3
	v_add_u32_e32 v4, 1, v1
	v_cmp_ge_u32_e32 vcc, v3, v2
	s_nop 1
	v_cndmask_b32_e32 v1, v1, v4, vcc
	v_sub_u32_e32 v4, v3, v2
	v_cndmask_b32_e32 v3, v3, v4, vcc
	v_add_u32_e32 v4, 1, v1
	v_cmp_ge_u32_e32 vcc, v3, v2
	v_add_u32_e32 v3, 1, v5
	s_nop 0
	v_cndmask_b32_e32 v1, v1, v4, vcc
	v_mul_lo_u32 v4, v2, v1
	v_add_u32_e32 v2, v4, v2
	v_cmp_ne_u32_e32 vcc, v3, v2
	s_and_saveexec_b64 s[6:7], vcc
	s_xor_b64 s[6:7], exec, s[6:7]
	s_cbranch_execz .LBB0_211
	s_waitcnt lgkmcnt(0)
	buffer_inv sc1
	v_mov_b32_e32 v0, 0x2000
	global_load_dword v0, v0, s[36:37] offset:1024 sc1
	s_add_u32 s62, s36, 0x2400
	s_addc_u32 s63, s37, 0
	s_waitcnt vmcnt(0)
	v_cmp_eq_u32_e32 vcc, v0, v1
	s_and_saveexec_b64 s[46:47], vcc
	s_cbranch_execz .LBB0_210
	s_add_u32 s50, s72, 0x80200
	s_addc_u32 s51, s73, 0
	s_mov_b32 s8, 1
	s_mov_b64 s[64:65], 0
	v_mov_b32_e32 v0, 0
	s_branch .LBB0_201

; __device__ __forceinline__ unsigned xb_ld(unsigned* p)              { return __hip_atomic_load(p, __ATOMIC_RELAXED, __HIP_MEMORY_SCOPE_AGENT); }
; #define XB_SPIN(cond, bar) do { unsigned _sp = 0; while (cond) { __builtin_amdgcn_s_sleep(1); \
;     if ((++_sp & 255u) == 0u) { if (xb_ld(&(bar)[XB_TMO])) break; if (_sp > XB_SPIN_CAP) { atomicAdd(&(bar)[XB_TMO], 1u); break; } } } } while (0)
; __device__ __forceinline__ void xcd_barrier(const XcdBarrier& b) {
;     ...
;             XB_SPIN(xb_ld(&bar[XB_XGEN(b.x)]) == gen, bar);
;             __builtin_amdgcn_fence(__ATOMIC_ACQUIRE, "agent");
;             asm volatile("s_waitcnt vmcnt(0)" ::: "memory");
.LBB0_210:
	s_or_b64 exec, exec, s[46:47]
	s_waitcnt vmcnt(0)
	s_nop 0
	s_waitcnt vmcnt(0)

; __device__ __forceinline__ unsigned xb_ld(unsigned* p)              { return __hip_atomic_load(p, __ATOMIC_RELAXED, __HIP_MEMORY_SCOPE_AGENT); }
; __device__ __forceinline__ unsigned xb_add(unsigned* p, unsigned v) { return __hip_atomic_fetch_add(p, v, __ATOMIC_RELAXED, __HIP_MEMORY_SCOPE_AGENT); }
; #define XB_SPIN(cond, bar) do { unsigned _sp = 0; while (cond) { __builtin_amdgcn_s_sleep(1); \
;     if ((++_sp & 255u) == 0u) { if (xb_ld(&(bar)[XB_TMO])) break; if (_sp > XB_SPIN_CAP) { atomicAdd(&(bar)[XB_TMO], 1u); break; } } } } while (0)
; __device__ __forceinline__ void xcd_barrier(const XcdBarrier& b) {
;     ...
;             if (og + 1u == (tg + 1u) * nx) xb_add(&bar[XB_TOPGEN], 1u);
;             else XB_SPIN(xb_ld(&bar[XB_TOPGEN]) == tg, bar);
;             __builtin_amdgcn_fence(__ATOMIC_ACQUIRE, "agent");
;             xb_add(&bar[XB_XGEN(b.x)], 1u);
;             asm volatile("s_waitcnt vmcnt(0)" ::: "memory");
.LBB0_228:
	s_or_b64 exec, exec, s[6:7]
	s_mov_b64 s[6:7], exec
	v_mbcnt_lo_u32_b32 v0, s6, 0
	v_mbcnt_hi_u32_b32 v0, s7, v0
	v_cmp_eq_u32_e32 vcc, 0, v0
	s_waitcnt vmcnt(0)
	s_nop 0
	s_and_saveexec_b64 s[28:29], vcc
	s_cbranch_execz .LBB0_230
	s_bcnt1_i32_b64 s6, s[6:7]
	v_mov_b32_e32 v0, 0x2000
	v_mov_b32_e32 v1, s6
	global_atomic_add v0, v1, s[36:37] offset:1024

; __device__ __forceinline__ unsigned xb_ld(unsigned* p)              { return __hip_atomic_load(p, __ATOMIC_RELAXED, __HIP_MEMORY_SCOPE_AGENT); }
; __device__ __forceinline__ unsigned xb_add(unsigned* p, unsigned v) { return __hip_atomic_fetch_add(p, v, __ATOMIC_RELAXED, __HIP_MEMORY_SCOPE_AGENT); }
; #define XB_SPIN(cond, bar) do { unsigned _sp = 0; while (cond) { __builtin_amdgcn_s_sleep(1); \
;     if ((++_sp & 255u) == 0u) { if (xb_ld(&(bar)[XB_TMO])) break; if (_sp > XB_SPIN_CAP) { atomicAdd(&(bar)[XB_TMO], 1u); break; } } } } while (0)
; __device__ __forceinline__ void xcd_barrier(const XcdBarrier& b) {
;     ...
;         const unsigned old = xb_add(&bar[XB_XSUB(b.x)], 1u);
;         const unsigned gen = old / nloc;
;         if (old + 1u == (gen + 1u) * nloc) {
;             __builtin_amdgcn_fence(__ATOMIC_RELEASE, "agent");
;             asm volatile("s_waitcnt vmcnt(0)" ::: "memory");
;             const unsigned og = xb_add(&bar[XB_TOP], 1u);
;             const unsigned tg = og / nx;
;             if (og + 1u == (tg + 1u) * nx) xb_add(&bar[XB_TOPGEN], 1u);
;             else XB_SPIN(xb_ld(&bar[XB_TOPGEN]) == tg, bar);
;             __builtin_amdgcn_fence(__ATOMIC_ACQUIRE, "agent");
;             xb_add(&bar[XB_XGEN(b.x)], 1u);
;             asm volatile("s_waitcnt vmcnt(0)" ::: "memory");
;         } else {
;             XB_SPIN(xb_ld(&bar[XB_XGEN(b.x)]) == gen, bar);
.LBB0_332:
	s_or_b64 exec, exec, s[28:29]
	v_cvt_f32_u32_e32 v4, v2
	s_waitcnt vmcnt(0)
	v_readfirstlane_b32 s6, v3
	v_sub_u32_e32 v3, 0, v2
	v_rcp_iflag_f32_e32 v4, v4
	v_add_u32_e32 v5, s6, v1
	v_mul_f32_e32 v4, 0x4f7ffffe, v4
	v_cvt_u32_f32_e32 v4, v4
	v_mul_lo_u32 v1, v3, v4
	v_mul_hi_u32 v1, v4, v1
	v_add_u32_e32 v1, v4, v1
	v_mul_hi_u32 v1, v5, v1
	v_mul_lo_u32 v3, v1, v2
	v_sub_u32_e32 v3, v5, v3
	v_add_u32_e32 v4, 1, v1
	v_cmp_ge_u32_e32 vcc, v3, v2
	s_nop 1
	v_cndmask_b32_e32 v1, v1, v4, vcc
	v_sub_u32_e32 v4, v3, v2
	v_cndmask_b32_e32 v3, v3, v4, vcc
	v_add_u32_e32 v4, 1, v1
	v_cmp_ge_u32_e32 vcc, v3, v2
	v_add_u32_e32 v3, 1, v5
	s_nop 0
	v_cndmask_b32_e32 v1, v1, v4, vcc
	v_mul_lo_u32 v4, v2, v1
	v_add_u32_e32 v2, v4, v2
	v_cmp_ne_u32_e32 vcc, v3, v2
	s_and_saveexec_b64 s[6:7], vcc
	s_xor_b64 s[6:7], exec, s[6:7]
	s_cbranch_execz .LBB0_346
	s_waitcnt lgkmcnt(0)
	buffer_inv sc1
	v_mov_b32_e32 v0, 0x2000
	global_load_dword v0, v0, s[40:41] offset:1024 sc1
	s_add_u32 s50, s40, 0x2400
	s_addc_u32 s51, s41, 0
	s_waitcnt vmcnt(0)
	v_cmp_eq_u32_e32 vcc, v0, v1
	s_and_saveexec_b64 s[42:43], vcc
	s_cbranch_execz .LBB0_345
	s_add_u32 s46, s72, 0x80200
	s_addc_u32 s47, s73, 0
	s_mov_b32 s8, 1
	s_mov_b64 s[52:53], 0
	v_mov_b32_e32 v0, 0
	s_branch .LBB0_336

; __device__ __forceinline__ unsigned xb_ld(unsigned* p)              { return __hip_atomic_load(p, __ATOMIC_RELAXED, __HIP_MEMORY_SCOPE_AGENT); }
; #define XB_SPIN(cond, bar) do { unsigned _sp = 0; while (cond) { __builtin_amdgcn_s_sleep(1); \
;     if ((++_sp & 255u) == 0u) { if (xb_ld(&(bar)[XB_TMO])) break; if (_sp > XB_SPIN_CAP) { atomicAdd(&(bar)[XB_TMO], 1u); break; } } } } while (0)
; __device__ __forceinline__ void xcd_barrier(const XcdBarrier& b) {
;     ...
;             XB_SPIN(xb_ld(&bar[XB_XGEN(b.x)]) == gen, bar);
;             __builtin_amdgcn_fence(__ATOMIC_ACQUIRE, "agent");
;             asm volatile("s_waitcnt vmcnt(0)" ::: "memory");
.LBB0_345:
	s_or_b64 exec, exec, s[42:43]
	s_waitcnt vmcnt(0)
	s_nop 0
	s_waitcnt vmcnt(0)

; __device__ __forceinline__ unsigned xb_ld(unsigned* p)              { return __hip_atomic_load(p, __ATOMIC_RELAXED, __HIP_MEMORY_SCOPE_AGENT); }
; __device__ __forceinline__ unsigned xb_add(unsigned* p, unsigned v) { return __hip_atomic_fetch_add(p, v, __ATOMIC_RELAXED, __HIP_MEMORY_SCOPE_AGENT); }
; #define XB_SPIN(cond, bar) do { unsigned _sp = 0; while (cond) { __builtin_amdgcn_s_sleep(1); \
;     if ((++_sp & 255u) == 0u) { if (xb_ld(&(bar)[XB_TMO])) break; if (_sp > XB_SPIN_CAP) { atomicAdd(&(bar)[XB_TMO], 1u); break; } } } } while (0)
; __device__ __forceinline__ void xcd_barrier(const XcdBarrier& b) {
;     ...
;             if (og + 1u == (tg + 1u) * nx) xb_add(&bar[XB_TOPGEN], 1u);
;             else XB_SPIN(xb_ld(&bar[XB_TOPGEN]) == tg, bar);
;             __builtin_amdgcn_fence(__ATOMIC_ACQUIRE, "agent");
;             xb_add(&bar[XB_XGEN(b.x)], 1u);
;             asm volatile("s_waitcnt vmcnt(0)" ::: "memory");
.LBB0_363:
	s_or_b64 exec, exec, s[6:7]
	s_mov_b64 s[6:7], exec
	v_mbcnt_lo_u32_b32 v0, s6, 0
	v_mbcnt_hi_u32_b32 v0, s7, v0
	v_cmp_eq_u32_e32 vcc, 0, v0
	s_waitcnt vmcnt(0)
	s_nop 0
	s_and_saveexec_b64 s[28:29], vcc
	s_cbranch_execz .LBB0_365
	s_bcnt1_i32_b64 s6, s[6:7]
	v_mov_b32_e32 v0, 0x2000
	v_mov_b32_e32 v1, s6
	global_atomic_add v0, v1, s[40:41] offset:1024

; __device__ __forceinline__ unsigned xb_ld(unsigned* p)              { return __hip_atomic_load(p, __ATOMIC_RELAXED, __HIP_MEMORY_SCOPE_AGENT); }
; __device__ __forceinline__ unsigned xb_add(unsigned* p, unsigned v) { return __hip_atomic_fetch_add(p, v, __ATOMIC_RELAXED, __HIP_MEMORY_SCOPE_AGENT); }
; #define XB_SPIN(cond, bar) do { unsigned _sp = 0; while (cond) { __builtin_amdgcn_s_sleep(1); \
;     if ((++_sp & 255u) == 0u) { if (xb_ld(&(bar)[XB_TMO])) break; if (_sp > XB_SPIN_CAP) { atomicAdd(&(bar)[XB_TMO], 1u); break; } } } } while (0)
; __device__ __forceinline__ void xcd_barrier(const XcdBarrier& b) {
;     ...
;         const unsigned old = xb_add(&bar[XB_XSUB(b.x)], 1u);
;         const unsigned gen = old / nloc;
;         if (old + 1u == (gen + 1u) * nloc) {
;             __builtin_amdgcn_fence(__ATOMIC_RELEASE, "agent");
;             asm volatile("s_waitcnt vmcnt(0)" ::: "memory");
;             const unsigned og = xb_add(&bar[XB_TOP], 1u);
;             const unsigned tg = og / nx;
;             if (og + 1u == (tg + 1u) * nx) xb_add(&bar[XB_TOPGEN], 1u);
;             else XB_SPIN(xb_ld(&bar[XB_TOPGEN]) == tg, bar);
;             __builtin_amdgcn_fence(__ATOMIC_ACQUIRE, "agent");
;             xb_add(&bar[XB_XGEN(b.x)], 1u);
;             asm volatile("s_waitcnt vmcnt(0)" ::: "memory");
;         } else {
;             XB_SPIN(xb_ld(&bar[XB_XGEN(b.x)]) == gen, bar);
.LBB0_429:
	s_or_b64 exec, exec, s[6:7]
	v_cvt_f32_u32_e32 v4, v2
	s_waitcnt vmcnt(0)
	v_readfirstlane_b32 s4, v3
	v_sub_u32_e32 v3, 0, v2
	v_rcp_iflag_f32_e32 v4, v4
	v_add_u32_e32 v5, s4, v1
	v_mul_f32_e32 v4, 0x4f7ffffe, v4
	v_cvt_u32_f32_e32 v4, v4
	v_mul_lo_u32 v1, v3, v4
	v_mul_hi_u32 v1, v4, v1
	v_add_u32_e32 v1, v4, v1
	v_mul_hi_u32 v1, v5, v1
	v_mul_lo_u32 v3, v1, v2
	v_sub_u32_e32 v3, v5, v3
	v_add_u32_e32 v4, 1, v1
	v_cmp_ge_u32_e32 vcc, v3, v2
	s_nop 1
	v_cndmask_b32_e32 v1, v1, v4, vcc
	v_sub_u32_e32 v4, v3, v2
	v_cndmask_b32_e32 v3, v3, v4, vcc
	v_add_u32_e32 v4, 1, v1
	v_cmp_ge_u32_e32 vcc, v3, v2
	v_add_u32_e32 v3, 1, v5
	s_nop 0
	v_cndmask_b32_e32 v1, v1, v4, vcc
	v_mul_lo_u32 v4, v2, v1
	v_add_u32_e32 v2, v4, v2
	v_cmp_ne_u32_e32 vcc, v3, v2
	s_and_saveexec_b64 s[4:5], vcc
	s_xor_b64 s[4:5], exec, s[4:5]
	s_cbranch_execz .LBB0_443
	s_waitcnt lgkmcnt(0)
	buffer_inv sc1
	v_mov_b32_e32 v0, 0x2000
	global_load_dword v0, v0, s[2:3] offset:1024 sc1
	s_add_u32 s46, s2, 0x2400
	s_addc_u32 s47, s3, 0
	s_waitcnt vmcnt(0)
	v_cmp_eq_u32_e32 vcc, v0, v1
	s_and_saveexec_b64 s[6:7], vcc
	s_cbranch_execz .LBB0_442
	s_add_u32 s40, s72, 0x80200
	s_addc_u32 s41, s73, 0
	s_mov_b32 s8, 1
	s_mov_b64 s[50:51], 0
	v_mov_b32_e32 v0, 0
	s_branch .LBB0_433

; __device__ __forceinline__ unsigned xb_ld(unsigned* p)              { return __hip_atomic_load(p, __ATOMIC_RELAXED, __HIP_MEMORY_SCOPE_AGENT); }
; __device__ __forceinline__ unsigned xb_add(unsigned* p, unsigned v) { return __hip_atomic_fetch_add(p, v, __ATOMIC_RELAXED, __HIP_MEMORY_SCOPE_AGENT); }
; #define XB_SPIN(cond, bar) do { unsigned _sp = 0; while (cond) { __builtin_amdgcn_s_sleep(1); \
;     if ((++_sp & 255u) == 0u) { if (xb_ld(&(bar)[XB_TMO])) break; if (_sp > XB_SPIN_CAP) { atomicAdd(&(bar)[XB_TMO], 1u); break; } } } } while (0)
; __device__ __forceinline__ void xcd_barrier(const XcdBarrier& b) {
;     ...
;             __builtin_amdgcn_fence(__ATOMIC_RELEASE, "agent");
;             asm volatile("s_waitcnt vmcnt(0)" ::: "memory");
;             const unsigned og = xb_add(&bar[XB_TOP], 1u);
;             const unsigned tg = og / nx;
;             if (og + 1u == (tg + 1u) * nx) xb_add(&bar[XB_TOPGEN], 1u);
;             else XB_SPIN(xb_ld(&bar[XB_TOPGEN]) == tg, bar);
;             __builtin_amdgcn_fence(__ATOMIC_ACQUIRE, "agent");
;             xb_add(&bar[XB_XGEN(b.x)], 1u);
;             asm volatile("s_waitcnt vmcnt(0)" ::: "memory");
;         } else {
;             XB_SPIN(xb_ld(&bar[XB_XGEN(b.x)]) == gen, bar);
;             __builtin_amdgcn_fence(__ATOMIC_ACQUIRE, "agent");
;             asm volatile("s_waitcnt vmcnt(0)" ::: "memory");
.LBB0_442:
	s_or_b64 exec, exec, s[6:7]
	s_waitcnt vmcnt(0)
	s_nop 0
	s_waitcnt vmcnt(0)
.LBB0_443:
	s_andn2_saveexec_b64 s[4:5], s[4:5]
	s_cbranch_execz .LBB0_463
	s_mov_b64 s[4:5], exec
	buffer_inv sc1
	buffer_wbl2 sc1
	s_waitcnt lgkmcnt(0)
	s_waitcnt vmcnt(0)
	v_mbcnt_lo_u32_b32 v1, s4, 0
	v_mbcnt_hi_u32_b32 v1, s5, v1
	v_cmp_eq_u32_e32 vcc, 0, v1
	s_and_saveexec_b64 s[6:7], vcc
	s_cbranch_execz .LBB0_446
	s_bcnt1_i32_b64 s4, s[4:5]
	v_mov_b32_e32 v2, 0x83000
	v_mov_b32_e32 v3, s4
	global_atomic_add v2, v2, v3, s[72:73] offset:1024 sc0

; __device__ __forceinline__ unsigned xb_ld(unsigned* p)              { return __hip_atomic_load(p, __ATOMIC_RELAXED, __HIP_MEMORY_SCOPE_AGENT); }
; __device__ __forceinline__ unsigned xb_add(unsigned* p, unsigned v) { return __hip_atomic_fetch_add(p, v, __ATOMIC_RELAXED, __HIP_MEMORY_SCOPE_AGENT); }
; #define XB_SPIN(cond, bar) do { unsigned _sp = 0; while (cond) { __builtin_amdgcn_s_sleep(1); \
;     if ((++_sp & 255u) == 0u) { if (xb_ld(&(bar)[XB_TMO])) break; if (_sp > XB_SPIN_CAP) { atomicAdd(&(bar)[XB_TMO], 1u); break; } } } } while (0)
; __device__ __forceinline__ void xcd_barrier(const XcdBarrier& b) {
;     ...
;             if (og + 1u == (tg + 1u) * nx) xb_add(&bar[XB_TOPGEN], 1u);
;             else XB_SPIN(xb_ld(&bar[XB_TOPGEN]) == tg, bar);
;             __builtin_amdgcn_fence(__ATOMIC_ACQUIRE, "agent");
;             xb_add(&bar[XB_XGEN(b.x)], 1u);
;             asm volatile("s_waitcnt vmcnt(0)" ::: "memory");
.LBB0_460:
	s_or_b64 exec, exec, s[4:5]
	s_mov_b64 s[4:5], exec
	v_mbcnt_lo_u32_b32 v0, s4, 0
	v_mbcnt_hi_u32_b32 v0, s5, v0
	v_cmp_eq_u32_e32 vcc, 0, v0
	s_waitcnt vmcnt(0)
	s_nop 0
	s_and_saveexec_b64 s[6:7], vcc
	s_cbranch_execz .LBB0_462
	s_bcnt1_i32_b64 s4, s[4:5]
	v_mov_b32_e32 v0, 0x2000
	v_mov_b32_e32 v1, s4
	global_atomic_add v0, v1, s[2:3] offset:1024

; __device__ __forceinline__ unsigned xb_ld(unsigned* p)              { return __hip_atomic_load(p, __ATOMIC_RELAXED, __HIP_MEMORY_SCOPE_AGENT); }
; __device__ __forceinline__ unsigned xb_add(unsigned* p, unsigned v) { return __hip_atomic_fetch_add(p, v, __ATOMIC_RELAXED, __HIP_MEMORY_SCOPE_AGENT); }
; #define XB_SPIN(cond, bar) do { unsigned _sp = 0; while (cond) { __builtin_amdgcn_s_sleep(1); \
;     if ((++_sp & 255u) == 0u) { if (xb_ld(&(bar)[XB_TMO])) break; if (_sp > XB_SPIN_CAP) { atomicAdd(&(bar)[XB_TMO], 1u); break; } } } } while (0)
; __device__ __forceinline__ void xcd_barrier(const XcdBarrier& b) {
;     ...
;         const unsigned old = xb_add(&bar[XB_XSUB(b.x)], 1u);
;         const unsigned gen = old / nloc;
;         if (old + 1u == (gen + 1u) * nloc) {
;             __builtin_amdgcn_fence(__ATOMIC_RELEASE, "agent");
;             asm volatile("s_waitcnt vmcnt(0)" ::: "memory");
;             const unsigned og = xb_add(&bar[XB_TOP], 1u);
;             const unsigned tg = og / nx;
;             if (og + 1u == (tg + 1u) * nx) xb_add(&bar[XB_TOPGEN], 1u);
;             else XB_SPIN(xb_ld(&bar[XB_TOPGEN]) == tg, bar);
;             __builtin_amdgcn_fence(__ATOMIC_ACQUIRE, "agent");
;             xb_add(&bar[XB_XGEN(b.x)], 1u);
;             asm volatile("s_waitcnt vmcnt(0)" ::: "memory");
;         } else {
;             XB_SPIN(xb_ld(&bar[XB_XGEN(b.x)]) == gen, bar);
.LBB0_540:
	s_or_b64 exec, exec, s[12:13]
	v_cvt_f32_u32_e32 v4, v2
	s_waitcnt vmcnt(0)
	v_readfirstlane_b32 s6, v3
	v_sub_u32_e32 v3, 0, v2
	v_rcp_iflag_f32_e32 v4, v4
	v_add_u32_e32 v5, s6, v1
	v_mul_f32_e32 v4, 0x4f7ffffe, v4
	v_cvt_u32_f32_e32 v4, v4
	v_mul_lo_u32 v1, v3, v4
	v_mul_hi_u32 v1, v4, v1
	v_add_u32_e32 v1, v4, v1
	v_mul_hi_u32 v1, v5, v1
	v_mul_lo_u32 v3, v1, v2
	v_sub_u32_e32 v3, v5, v3
	v_add_u32_e32 v4, 1, v1
	v_cmp_ge_u32_e32 vcc, v3, v2
	s_nop 1
	v_cndmask_b32_e32 v1, v1, v4, vcc
	v_sub_u32_e32 v4, v3, v2
	v_cndmask_b32_e32 v3, v3, v4, vcc
	v_add_u32_e32 v4, 1, v1
	v_cmp_ge_u32_e32 vcc, v3, v2
	v_add_u32_e32 v3, 1, v5
	s_nop 0
	v_cndmask_b32_e32 v1, v1, v4, vcc
	v_mul_lo_u32 v4, v2, v1
	v_add_u32_e32 v2, v4, v2
	v_cmp_ne_u32_e32 vcc, v3, v2
	s_and_saveexec_b64 s[6:7], vcc
	s_xor_b64 s[6:7], exec, s[6:7]
	s_cbranch_execz .LBB0_554
	s_waitcnt lgkmcnt(0)
	buffer_inv sc1
	v_mov_b32_e32 v0, 0x2000
	global_load_dword v0, v0, s[4:5] offset:1024 sc1
	s_add_u32 s38, s4, 0x2400
	s_addc_u32 s39, s5, 0
	s_waitcnt vmcnt(0)
	v_cmp_eq_u32_e32 vcc, v0, v1
	s_and_saveexec_b64 s[12:13], vcc
	s_cbranch_execz .LBB0_553
	s_add_u32 s22, s72, 0x80200
	s_addc_u32 s23, s73, 0
	s_mov_b32 s8, 1
	s_mov_b64 s[42:43], 0
	v_mov_b32_e32 v0, 0
	s_branch .LBB0_544

; __device__ __forceinline__ unsigned xb_ld(unsigned* p)              { return __hip_atomic_load(p, __ATOMIC_RELAXED, __HIP_MEMORY_SCOPE_AGENT); }
; __device__ __forceinline__ unsigned xb_add(unsigned* p, unsigned v) { return __hip_atomic_fetch_add(p, v, __ATOMIC_RELAXED, __HIP_MEMORY_SCOPE_AGENT); }
; #define XB_SPIN(cond, bar) do { unsigned _sp = 0; while (cond) { __builtin_amdgcn_s_sleep(1); \
;     if ((++_sp & 255u) == 0u) { if (xb_ld(&(bar)[XB_TMO])) break; if (_sp > XB_SPIN_CAP) { atomicAdd(&(bar)[XB_TMO], 1u); break; } } } } while (0)
; __device__ __forceinline__ void xcd_barrier(const XcdBarrier& b) {
;     ...
;             __builtin_amdgcn_fence(__ATOMIC_RELEASE, "agent");
;             asm volatile("s_waitcnt vmcnt(0)" ::: "memory");
;             const unsigned og = xb_add(&bar[XB_TOP], 1u);
;             const unsigned tg = og / nx;
;             if (og + 1u == (tg + 1u) * nx) xb_add(&bar[XB_TOPGEN], 1u);
;             else XB_SPIN(xb_ld(&bar[XB_TOPGEN]) == tg, bar);
;             __builtin_amdgcn_fence(__ATOMIC_ACQUIRE, "agent");
;             xb_add(&bar[XB_XGEN(b.x)], 1u);
;             asm volatile("s_waitcnt vmcnt(0)" ::: "memory");
;         } else {
;             XB_SPIN(xb_ld(&bar[XB_XGEN(b.x)]) == gen, bar);
;             __builtin_amdgcn_fence(__ATOMIC_ACQUIRE, "agent");
;             asm volatile("s_waitcnt vmcnt(0)" ::: "memory");
.LBB0_553:
	s_or_b64 exec, exec, s[12:13]
	s_waitcnt vmcnt(0)
	s_nop 0
	s_waitcnt vmcnt(0)
.LBB0_554:
	s_andn2_saveexec_b64 s[6:7], s[6:7]
	s_cbranch_execz .LBB0_574
	s_mov_b64 s[6:7], exec
	buffer_inv sc1
	buffer_wbl2 sc1
	s_waitcnt lgkmcnt(0)
	s_waitcnt vmcnt(0)
	v_mbcnt_lo_u32_b32 v1, s6, 0
	v_mbcnt_hi_u32_b32 v1, s7, v1
	v_cmp_eq_u32_e32 vcc, 0, v1
	s_and_saveexec_b64 s[12:13], vcc
	s_cbranch_execz .LBB0_557
	s_bcnt1_i32_b64 s6, s[6:7]
	v_mov_b32_e32 v2, 0x83000
	v_mov_b32_e32 v3, s6
	global_atomic_add v2, v2, v3, s[72:73] offset:1024 sc0

; __device__ __forceinline__ unsigned xb_ld(unsigned* p)              { return __hip_atomic_load(p, __ATOMIC_RELAXED, __HIP_MEMORY_SCOPE_AGENT); }
; __device__ __forceinline__ unsigned xb_add(unsigned* p, unsigned v) { return __hip_atomic_fetch_add(p, v, __ATOMIC_RELAXED, __HIP_MEMORY_SCOPE_AGENT); }
; #define XB_SPIN(cond, bar) do { unsigned _sp = 0; while (cond) { __builtin_amdgcn_s_sleep(1); \
;     if ((++_sp & 255u) == 0u) { if (xb_ld(&(bar)[XB_TMO])) break; if (_sp > XB_SPIN_CAP) { atomicAdd(&(bar)[XB_TMO], 1u); break; } } } } while (0)
; __device__ __forceinline__ void xcd_barrier(const XcdBarrier& b) {
;     ...
;             if (og + 1u == (tg + 1u) * nx) xb_add(&bar[XB_TOPGEN], 1u);
;             else XB_SPIN(xb_ld(&bar[XB_TOPGEN]) == tg, bar);
;             __builtin_amdgcn_fence(__ATOMIC_ACQUIRE, "agent");
;             xb_add(&bar[XB_XGEN(b.x)], 1u);
;             asm volatile("s_waitcnt vmcnt(0)" ::: "memory");
.LBB0_571:
	s_or_b64 exec, exec, s[6:7]
	s_mov_b64 s[6:7], exec
	v_mbcnt_lo_u32_b32 v0, s6, 0
	v_mbcnt_hi_u32_b32 v0, s7, v0
	v_cmp_eq_u32_e32 vcc, 0, v0
	s_waitcnt vmcnt(0)
	s_nop 0
	s_and_saveexec_b64 s[12:13], vcc
	s_cbranch_execz .LBB0_573
	s_bcnt1_i32_b64 s6, s[6:7]
	v_mov_b32_e32 v0, 0x2000
	v_mov_b32_e32 v1, s6
	global_atomic_add v0, v1, s[4:5] offset:1024

; __device__ __forceinline__ unsigned xb_ld(unsigned* p)              { return __hip_atomic_load(p, __ATOMIC_RELAXED, __HIP_MEMORY_SCOPE_AGENT); }
; __device__ __forceinline__ unsigned xb_add(unsigned* p, unsigned v) { return __hip_atomic_fetch_add(p, v, __ATOMIC_RELAXED, __HIP_MEMORY_SCOPE_AGENT); }
; #define XB_SPIN(cond, bar) do { unsigned _sp = 0; while (cond) { __builtin_amdgcn_s_sleep(1); \
;     if ((++_sp & 255u) == 0u) { if (xb_ld(&(bar)[XB_TMO])) break; if (_sp > XB_SPIN_CAP) { atomicAdd(&(bar)[XB_TMO], 1u); break; } } } } while (0)
; __device__ __forceinline__ void xcd_barrier(const XcdBarrier& b) {
;     ...
;         const unsigned old = xb_add(&bar[XB_XSUB(b.x)], 1u);
;         const unsigned gen = old / nloc;
;         if (old + 1u == (gen + 1u) * nloc) {
;             __builtin_amdgcn_fence(__ATOMIC_RELEASE, "agent");
;             asm volatile("s_waitcnt vmcnt(0)" ::: "memory");
;             const unsigned og = xb_add(&bar[XB_TOP], 1u);
;             const unsigned tg = og / nx;
;             if (og + 1u == (tg + 1u) * nx) xb_add(&bar[XB_TOPGEN], 1u);
;             else XB_SPIN(xb_ld(&bar[XB_TOPGEN]) == tg, bar);
;             __builtin_amdgcn_fence(__ATOMIC_ACQUIRE, "agent");
;             xb_add(&bar[XB_XGEN(b.x)], 1u);
;             asm volatile("s_waitcnt vmcnt(0)" ::: "memory");
;         } else {
;             XB_SPIN(xb_ld(&bar[XB_XGEN(b.x)]) == gen, bar);
.LBB0_637:
	s_or_b64 exec, exec, s[12:13]
	v_cvt_f32_u32_e32 v4, v2
	s_waitcnt vmcnt(0)
	v_readfirstlane_b32 s6, v3
	v_sub_u32_e32 v3, 0, v2
	v_rcp_iflag_f32_e32 v4, v4
	v_add_u32_e32 v5, s6, v1
	v_mul_f32_e32 v4, 0x4f7ffffe, v4
	v_cvt_u32_f32_e32 v4, v4
	v_mul_lo_u32 v1, v3, v4
	v_mul_hi_u32 v1, v4, v1
	v_add_u32_e32 v1, v4, v1
	v_mul_hi_u32 v1, v5, v1
	v_mul_lo_u32 v3, v1, v2
	v_sub_u32_e32 v3, v5, v3
	v_add_u32_e32 v4, 1, v1
	v_cmp_ge_u32_e32 vcc, v3, v2
	s_nop 1
	v_cndmask_b32_e32 v1, v1, v4, vcc
	v_sub_u32_e32 v4, v3, v2
	v_cndmask_b32_e32 v3, v3, v4, vcc
	v_add_u32_e32 v4, 1, v1
	v_cmp_ge_u32_e32 vcc, v3, v2
	v_add_u32_e32 v3, 1, v5
	s_nop 0
	v_cndmask_b32_e32 v1, v1, v4, vcc
	v_mul_lo_u32 v4, v2, v1
	v_add_u32_e32 v2, v4, v2
	v_cmp_ne_u32_e32 vcc, v3, v2
	s_and_saveexec_b64 s[6:7], vcc
	s_xor_b64 s[6:7], exec, s[6:7]
	s_cbranch_execz .LBB0_651
	s_waitcnt lgkmcnt(0)
	buffer_inv sc1
	v_mov_b32_e32 v0, 0x2000
	global_load_dword v0, v0, s[4:5] offset:1024 sc1
	s_add_u32 s40, s4, 0x2400
	s_addc_u32 s41, s5, 0
	s_waitcnt vmcnt(0)
	v_cmp_eq_u32_e32 vcc, v0, v1
	s_and_saveexec_b64 s[12:13], vcc
	s_cbranch_execz .LBB0_650
	s_add_u32 s22, s72, 0x80200
	s_addc_u32 s23, s73, 0
	s_mov_b32 s8, 1
	s_mov_b64 s[42:43], 0
	v_mov_b32_e32 v0, 0
	s_branch .LBB0_641

; __device__ __forceinline__ unsigned xb_ld(unsigned* p)              { return __hip_atomic_load(p, __ATOMIC_RELAXED, __HIP_MEMORY_SCOPE_AGENT); }
; __device__ __forceinline__ unsigned xb_add(unsigned* p, unsigned v) { return __hip_atomic_fetch_add(p, v, __ATOMIC_RELAXED, __HIP_MEMORY_SCOPE_AGENT); }
; #define XB_SPIN(cond, bar) do { unsigned _sp = 0; while (cond) { __builtin_amdgcn_s_sleep(1); \
;     if ((++_sp & 255u) == 0u) { if (xb_ld(&(bar)[XB_TMO])) break; if (_sp > XB_SPIN_CAP) { atomicAdd(&(bar)[XB_TMO], 1u); break; } } } } while (0)
; __device__ __forceinline__ void xcd_barrier(const XcdBarrier& b) {
;     ...
;         const unsigned old = xb_add(&bar[XB_XSUB(b.x)], 1u);
;         const unsigned gen = old / nloc;
;         if (old + 1u == (gen + 1u) * nloc) {
;             __builtin_amdgcn_fence(__ATOMIC_RELEASE, "agent");
;             asm volatile("s_waitcnt vmcnt(0)" ::: "memory");
;             const unsigned og = xb_add(&bar[XB_TOP], 1u);
;             const unsigned tg = og / nx;
;             if (og + 1u == (tg + 1u) * nx) xb_add(&bar[XB_TOPGEN], 1u);
;             else XB_SPIN(xb_ld(&bar[XB_TOPGEN]) == tg, bar);
;             __builtin_amdgcn_fence(__ATOMIC_ACQUIRE, "agent");
;             xb_add(&bar[XB_XGEN(b.x)], 1u);
;             asm volatile("s_waitcnt vmcnt(0)" ::: "memory");
;         } else {
;             XB_SPIN(xb_ld(&bar[XB_XGEN(b.x)]) == gen, bar);
.LBB0_811:
	s_or_b64 exec, exec, s[24:25]
	v_cvt_f32_u32_e32 v4, v2
	s_waitcnt vmcnt(0)
	v_readfirstlane_b32 s6, v3
	v_sub_u32_e32 v3, 0, v2
	v_rcp_iflag_f32_e32 v4, v4
	v_add_u32_e32 v5, s6, v1
	v_mul_f32_e32 v4, 0x4f7ffffe, v4
	v_cvt_u32_f32_e32 v4, v4
	v_mul_lo_u32 v1, v3, v4
	v_mul_hi_u32 v1, v4, v1
	v_add_u32_e32 v1, v4, v1
	v_mul_hi_u32 v1, v5, v1
	v_mul_lo_u32 v3, v1, v2
	v_sub_u32_e32 v3, v5, v3
	v_add_u32_e32 v4, 1, v1
	v_cmp_ge_u32_e32 vcc, v3, v2
	s_nop 1
	v_cndmask_b32_e32 v1, v1, v4, vcc
	v_sub_u32_e32 v4, v3, v2
	v_cndmask_b32_e32 v3, v3, v4, vcc
	v_add_u32_e32 v4, 1, v1
	v_cmp_ge_u32_e32 vcc, v3, v2
	v_add_u32_e32 v3, 1, v5
	s_nop 0
	v_cndmask_b32_e32 v1, v1, v4, vcc
	v_mul_lo_u32 v4, v2, v1
	v_add_u32_e32 v2, v4, v2
	v_cmp_ne_u32_e32 vcc, v3, v2
	s_and_saveexec_b64 s[6:7], vcc
	s_xor_b64 s[6:7], exec, s[6:7]
	s_cbranch_execz .LBB0_825
	s_waitcnt lgkmcnt(0)
	buffer_inv sc1
	v_mov_b32_e32 v0, 0x2000
	global_load_dword v0, v0, s[4:5] offset:1024 sc1
	s_add_u32 s38, s4, 0x2400
	s_addc_u32 s39, s5, 0
	s_waitcnt vmcnt(0)
	v_cmp_eq_u32_e32 vcc, v0, v1
	s_and_saveexec_b64 s[24:25], vcc
	s_cbranch_execz .LBB0_824
	s_add_u32 s26, s72, 0x80200
	s_addc_u32 s27, s73, 0
	s_mov_b32 s8, 1
	s_mov_b64 s[40:41], 0
	v_mov_b32_e32 v0, 0
	s_branch .LBB0_815

; __device__ __forceinline__ unsigned xb_ld(unsigned* p)              { return __hip_atomic_load(p, __ATOMIC_RELAXED, __HIP_MEMORY_SCOPE_AGENT); }
; __device__ __forceinline__ unsigned xb_add(unsigned* p, unsigned v) { return __hip_atomic_fetch_add(p, v, __ATOMIC_RELAXED, __HIP_MEMORY_SCOPE_AGENT); }
; #define XB_SPIN(cond, bar) do { unsigned _sp = 0; while (cond) { __builtin_amdgcn_s_sleep(1); \
;     if ((++_sp & 255u) == 0u) { if (xb_ld(&(bar)[XB_TMO])) break; if (_sp > XB_SPIN_CAP) { atomicAdd(&(bar)[XB_TMO], 1u); break; } } } } while (0)
; __device__ __forceinline__ void xcd_barrier(const XcdBarrier& b) {
;     ...
;             __builtin_amdgcn_fence(__ATOMIC_RELEASE, "agent");
;             asm volatile("s_waitcnt vmcnt(0)" ::: "memory");
;             const unsigned og = xb_add(&bar[XB_TOP], 1u);
;             const unsigned tg = og / nx;
;             if (og + 1u == (tg + 1u) * nx) xb_add(&bar[XB_TOPGEN], 1u);
;             else XB_SPIN(xb_ld(&bar[XB_TOPGEN]) == tg, bar);
;             __builtin_amdgcn_fence(__ATOMIC_ACQUIRE, "agent");
;             xb_add(&bar[XB_XGEN(b.x)], 1u);
;             asm volatile("s_waitcnt vmcnt(0)" ::: "memory");
;         } else {
;             XB_SPIN(xb_ld(&bar[XB_XGEN(b.x)]) == gen, bar);
;             __builtin_amdgcn_fence(__ATOMIC_ACQUIRE, "agent");
;             asm volatile("s_waitcnt vmcnt(0)" ::: "memory");
.LBB0_824:
	s_or_b64 exec, exec, s[24:25]
	s_waitcnt vmcnt(0)
	s_nop 0
	s_waitcnt vmcnt(0)
.LBB0_825:
	s_andn2_saveexec_b64 s[6:7], s[6:7]
	s_cbranch_execz .LBB0_845
	s_mov_b64 s[6:7], exec
	buffer_inv sc1
	buffer_wbl2 sc1
	s_waitcnt lgkmcnt(0)
	s_waitcnt vmcnt(0)
	v_mbcnt_lo_u32_b32 v1, s6, 0
	v_mbcnt_hi_u32_b32 v1, s7, v1
	v_cmp_eq_u32_e32 vcc, 0, v1
	s_and_saveexec_b64 s[24:25], vcc
	s_cbranch_execz .LBB0_828
	s_bcnt1_i32_b64 s6, s[6:7]
	v_mov_b32_e32 v2, 0x83000
	v_mov_b32_e32 v3, s6
	global_atomic_add v2, v2, v3, s[72:73] offset:1024 sc0

; __device__ __forceinline__ unsigned xb_ld(unsigned* p)              { return __hip_atomic_load(p, __ATOMIC_RELAXED, __HIP_MEMORY_SCOPE_AGENT); }
; __device__ __forceinline__ unsigned xb_add(unsigned* p, unsigned v) { return __hip_atomic_fetch_add(p, v, __ATOMIC_RELAXED, __HIP_MEMORY_SCOPE_AGENT); }
; #define XB_SPIN(cond, bar) do { unsigned _sp = 0; while (cond) { __builtin_amdgcn_s_sleep(1); \
;     if ((++_sp & 255u) == 0u) { if (xb_ld(&(bar)[XB_TMO])) break; if (_sp > XB_SPIN_CAP) { atomicAdd(&(bar)[XB_TMO], 1u); break; } } } } while (0)
; __device__ __forceinline__ void xcd_barrier(const XcdBarrier& b) {
;     ...
;             if (og + 1u == (tg + 1u) * nx) xb_add(&bar[XB_TOPGEN], 1u);
;             else XB_SPIN(xb_ld(&bar[XB_TOPGEN]) == tg, bar);
;             __builtin_amdgcn_fence(__ATOMIC_ACQUIRE, "agent");
;             xb_add(&bar[XB_XGEN(b.x)], 1u);
;             asm volatile("s_waitcnt vmcnt(0)" ::: "memory");
.LBB0_842:
	s_or_b64 exec, exec, s[6:7]
	s_mov_b64 s[6:7], exec
	v_mbcnt_lo_u32_b32 v0, s6, 0
	v_mbcnt_hi_u32_b32 v0, s7, v0
	v_cmp_eq_u32_e32 vcc, 0, v0
	s_waitcnt vmcnt(0)
	s_nop 0
	s_and_saveexec_b64 s[24:25], vcc
	s_cbranch_execz .LBB0_844
	s_bcnt1_i32_b64 s6, s[6:7]
	v_mov_b32_e32 v0, 0x2000
	v_mov_b32_e32 v1, s6
	global_atomic_add v0, v1, s[4:5] offset:1024

; __device__ __forceinline__ unsigned xb_ld(unsigned* p)              { return __hip_atomic_load(p, __ATOMIC_RELAXED, __HIP_MEMORY_SCOPE_AGENT); }
; __device__ __forceinline__ unsigned xb_add(unsigned* p, unsigned v) { return __hip_atomic_fetch_add(p, v, __ATOMIC_RELAXED, __HIP_MEMORY_SCOPE_AGENT); }
; #define XB_SPIN(cond, bar) do { unsigned _sp = 0; while (cond) { __builtin_amdgcn_s_sleep(1); \
;     if ((++_sp & 255u) == 0u) { if (xb_ld(&(bar)[XB_TMO])) break; if (_sp > XB_SPIN_CAP) { atomicAdd(&(bar)[XB_TMO], 1u); break; } } } } while (0)
; __device__ __forceinline__ void xcd_barrier(const XcdBarrier& b) {
;     ...
;         const unsigned old = xb_add(&bar[XB_XSUB(b.x)], 1u);
;         const unsigned gen = old / nloc;
;         if (old + 1u == (gen + 1u) * nloc) {
;             __builtin_amdgcn_fence(__ATOMIC_RELEASE, "agent");
;             asm volatile("s_waitcnt vmcnt(0)" ::: "memory");
;             const unsigned og = xb_add(&bar[XB_TOP], 1u);
;             const unsigned tg = og / nx;
;             if (og + 1u == (tg + 1u) * nx) xb_add(&bar[XB_TOPGEN], 1u);
;             else XB_SPIN(xb_ld(&bar[XB_TOPGEN]) == tg, bar);
;             __builtin_amdgcn_fence(__ATOMIC_ACQUIRE, "agent");
;             xb_add(&bar[XB_XGEN(b.x)], 1u);
;             asm volatile("s_waitcnt vmcnt(0)" ::: "memory");
;         } else {
;             XB_SPIN(xb_ld(&bar[XB_XGEN(b.x)]) == gen, bar);
.LBB0_1029:
	s_or_b64 exec, exec, s[14:15]
	v_cvt_f32_u32_e32 v4, v2
	s_waitcnt vmcnt(0)
	v_readfirstlane_b32 s6, v3
	v_sub_u32_e32 v3, 0, v2
	v_rcp_iflag_f32_e32 v4, v4
	v_add_u32_e32 v5, s6, v1
	v_mul_f32_e32 v4, 0x4f7ffffe, v4
	v_cvt_u32_f32_e32 v4, v4
	v_mul_lo_u32 v1, v3, v4
	v_mul_hi_u32 v1, v4, v1
	v_add_u32_e32 v1, v4, v1
	v_mul_hi_u32 v1, v5, v1
	v_mul_lo_u32 v3, v1, v2
	v_sub_u32_e32 v3, v5, v3
	v_add_u32_e32 v4, 1, v1
	v_cmp_ge_u32_e32 vcc, v3, v2
	s_nop 1
	v_cndmask_b32_e32 v1, v1, v4, vcc
	v_sub_u32_e32 v4, v3, v2
	v_cndmask_b32_e32 v3, v3, v4, vcc
	v_add_u32_e32 v4, 1, v1
	v_cmp_ge_u32_e32 vcc, v3, v2
	v_add_u32_e32 v3, 1, v5
	s_nop 0
	v_cndmask_b32_e32 v1, v1, v4, vcc
	v_mul_lo_u32 v4, v2, v1
	v_add_u32_e32 v2, v4, v2
	v_cmp_ne_u32_e32 vcc, v3, v2
	s_and_saveexec_b64 s[6:7], vcc
	s_xor_b64 s[6:7], exec, s[6:7]
	s_cbranch_execz .LBB0_1043
	s_waitcnt lgkmcnt(0)
	buffer_inv sc1
	v_mov_b32_e32 v0, 0x2000
	global_load_dword v0, v0, s[4:5] offset:1024 sc1
	s_add_u32 s18, s4, 0x2400
	s_addc_u32 s19, s5, 0
	s_waitcnt vmcnt(0)
	v_cmp_eq_u32_e32 vcc, v0, v1
	s_and_saveexec_b64 s[14:15], vcc
	s_cbranch_execz .LBB0_1042
	s_add_u32 s16, s72, 0x80200
	s_addc_u32 s17, s73, 0
	s_mov_b32 s8, 1
	s_mov_b64 s[20:21], 0
	v_mov_b32_e32 v0, 0
	s_branch .LBB0_1033

; __device__ __forceinline__ unsigned xb_ld(unsigned* p)              { return __hip_atomic_load(p, __ATOMIC_RELAXED, __HIP_MEMORY_SCOPE_AGENT); }
; __device__ __forceinline__ unsigned xb_add(unsigned* p, unsigned v) { return __hip_atomic_fetch_add(p, v, __ATOMIC_RELAXED, __HIP_MEMORY_SCOPE_AGENT); }
; #define XB_SPIN(cond, bar) do { unsigned _sp = 0; while (cond) { __builtin_amdgcn_s_sleep(1); \
;     if ((++_sp & 255u) == 0u) { if (xb_ld(&(bar)[XB_TMO])) break; if (_sp > XB_SPIN_CAP) { atomicAdd(&(bar)[XB_TMO], 1u); break; } } } } while (0)
; __device__ __forceinline__ void xcd_barrier(const XcdBarrier& b) {
;     ...
;             __builtin_amdgcn_fence(__ATOMIC_RELEASE, "agent");
;             asm volatile("s_waitcnt vmcnt(0)" ::: "memory");
;             const unsigned og = xb_add(&bar[XB_TOP], 1u);
;             const unsigned tg = og / nx;
;             if (og + 1u == (tg + 1u) * nx) xb_add(&bar[XB_TOPGEN], 1u);
;             else XB_SPIN(xb_ld(&bar[XB_TOPGEN]) == tg, bar);
;             __builtin_amdgcn_fence(__ATOMIC_ACQUIRE, "agent");
;             xb_add(&bar[XB_XGEN(b.x)], 1u);
;             asm volatile("s_waitcnt vmcnt(0)" ::: "memory");
;         } else {
;             XB_SPIN(xb_ld(&bar[XB_XGEN(b.x)]) == gen, bar);
;             __builtin_amdgcn_fence(__ATOMIC_ACQUIRE, "agent");
;             asm volatile("s_waitcnt vmcnt(0)" ::: "memory");
.LBB0_1042:
	s_or_b64 exec, exec, s[14:15]
	s_waitcnt vmcnt(0)
	s_nop 0
	s_waitcnt vmcnt(0)
.LBB0_1043:
	s_andn2_saveexec_b64 s[6:7], s[6:7]
	s_cbranch_execz .LBB0_1063
	s_mov_b64 s[6:7], exec
	buffer_inv sc1
	buffer_wbl2 sc1
	s_waitcnt lgkmcnt(0)
	s_waitcnt vmcnt(0)
	v_mbcnt_lo_u32_b32 v1, s6, 0
	v_mbcnt_hi_u32_b32 v1, s7, v1
	v_cmp_eq_u32_e32 vcc, 0, v1
	s_and_saveexec_b64 s[14:15], vcc
	s_cbranch_execz .LBB0_1046
	s_bcnt1_i32_b64 s6, s[6:7]
	v_mov_b32_e32 v2, 0x83000
	v_mov_b32_e32 v3, s6
	global_atomic_add v2, v2, v3, s[72:73] offset:1024 sc0

; __device__ __forceinline__ unsigned xb_ld(unsigned* p)              { return __hip_atomic_load(p, __ATOMIC_RELAXED, __HIP_MEMORY_SCOPE_AGENT); }
; __device__ __forceinline__ unsigned xb_add(unsigned* p, unsigned v) { return __hip_atomic_fetch_add(p, v, __ATOMIC_RELAXED, __HIP_MEMORY_SCOPE_AGENT); }
; #define XB_SPIN(cond, bar) do { unsigned _sp = 0; while (cond) { __builtin_amdgcn_s_sleep(1); \
;     if ((++_sp & 255u) == 0u) { if (xb_ld(&(bar)[XB_TMO])) break; if (_sp > XB_SPIN_CAP) { atomicAdd(&(bar)[XB_TMO], 1u); break; } } } } while (0)
; __device__ __forceinline__ void xcd_barrier(const XcdBarrier& b) {
;     ...
;             if (og + 1u == (tg + 1u) * nx) xb_add(&bar[XB_TOPGEN], 1u);
;             else XB_SPIN(xb_ld(&bar[XB_TOPGEN]) == tg, bar);
;             __builtin_amdgcn_fence(__ATOMIC_ACQUIRE, "agent");
;             xb_add(&bar[XB_XGEN(b.x)], 1u);
;             asm volatile("s_waitcnt vmcnt(0)" ::: "memory");
.LBB0_1060:
	s_or_b64 exec, exec, s[6:7]
	s_mov_b64 s[6:7], exec
	v_mbcnt_lo_u32_b32 v0, s6, 0
	v_mbcnt_hi_u32_b32 v0, s7, v0
	v_cmp_eq_u32_e32 vcc, 0, v0
	s_waitcnt vmcnt(0)
	s_nop 0
	s_and_saveexec_b64 s[14:15], vcc
	s_cbranch_execz .LBB0_1062
	s_bcnt1_i32_b64 s6, s[6:7]
	v_mov_b32_e32 v0, 0x2000
	v_mov_b32_e32 v1, s6
	global_atomic_add v0, v1, s[4:5] offset:1024

; __device__ __forceinline__ unsigned xb_ld(unsigned* p)              { return __hip_atomic_load(p, __ATOMIC_RELAXED, __HIP_MEMORY_SCOPE_AGENT); }
; __device__ __forceinline__ unsigned xb_add(unsigned* p, unsigned v) { return __hip_atomic_fetch_add(p, v, __ATOMIC_RELAXED, __HIP_MEMORY_SCOPE_AGENT); }
; #define XB_SPIN(cond, bar) do { unsigned _sp = 0; while (cond) { __builtin_amdgcn_s_sleep(1); \
;     if ((++_sp & 255u) == 0u) { if (xb_ld(&(bar)[XB_TMO])) break; if (_sp > XB_SPIN_CAP) { atomicAdd(&(bar)[XB_TMO], 1u); break; } } } } while (0)
; __device__ __forceinline__ void xcd_barrier(const XcdBarrier& b) {
;     ...
;         const unsigned old = xb_add(&bar[XB_XSUB(b.x)], 1u);
;         const unsigned gen = old / nloc;
;         if (old + 1u == (gen + 1u) * nloc) {
;             __builtin_amdgcn_fence(__ATOMIC_RELEASE, "agent");
;             asm volatile("s_waitcnt vmcnt(0)" ::: "memory");
;             const unsigned og = xb_add(&bar[XB_TOP], 1u);
;             const unsigned tg = og / nx;
;             if (og + 1u == (tg + 1u) * nx) xb_add(&bar[XB_TOPGEN], 1u);
;             else XB_SPIN(xb_ld(&bar[XB_TOPGEN]) == tg, bar);
;             __builtin_amdgcn_fence(__ATOMIC_ACQUIRE, "agent");
;             xb_add(&bar[XB_XGEN(b.x)], 1u);
;             asm volatile("s_waitcnt vmcnt(0)" ::: "memory");
;         } else {
;             XB_SPIN(xb_ld(&bar[XB_XGEN(b.x)]) == gen, bar);
.LBB0_1126:
	s_or_b64 exec, exec, s[14:15]
	v_cvt_f32_u32_e32 v4, v2
	s_waitcnt vmcnt(0)
	v_readfirstlane_b32 s6, v3
	v_sub_u32_e32 v3, 0, v2
	v_rcp_iflag_f32_e32 v4, v4
	v_add_u32_e32 v5, s6, v1
	v_mul_f32_e32 v4, 0x4f7ffffe, v4
	v_cvt_u32_f32_e32 v4, v4
	v_mul_lo_u32 v1, v3, v4
	v_mul_hi_u32 v1, v4, v1
	v_add_u32_e32 v1, v4, v1
	v_mul_hi_u32 v1, v5, v1
	v_mul_lo_u32 v3, v1, v2
	v_sub_u32_e32 v3, v5, v3
	v_add_u32_e32 v4, 1, v1
	v_cmp_ge_u32_e32 vcc, v3, v2
	s_nop 1
	v_cndmask_b32_e32 v1, v1, v4, vcc
	v_sub_u32_e32 v4, v3, v2
	v_cndmask_b32_e32 v3, v3, v4, vcc
	v_add_u32_e32 v4, 1, v1
	v_cmp_ge_u32_e32 vcc, v3, v2
	v_add_u32_e32 v3, 1, v5
	s_nop 0
	v_cndmask_b32_e32 v1, v1, v4, vcc
	v_mul_lo_u32 v4, v2, v1
	v_add_u32_e32 v2, v4, v2
	v_cmp_ne_u32_e32 vcc, v3, v2
	s_and_saveexec_b64 s[6:7], vcc
	s_xor_b64 s[6:7], exec, s[6:7]
	s_cbranch_execz .LBB0_1140
	s_waitcnt lgkmcnt(0)
	buffer_inv sc1
	v_mov_b32_e32 v0, 0x2000
	global_load_dword v0, v0, s[2:3] offset:1024 sc1
	s_add_u32 s18, s2, 0x2400
	s_addc_u32 s19, s3, 0
	s_waitcnt vmcnt(0)
	v_cmp_eq_u32_e32 vcc, v0, v1
	s_and_saveexec_b64 s[14:15], vcc
	s_cbranch_execz .LBB0_1139
	s_add_u32 s16, s72, 0x80200
	s_addc_u32 s17, s73, 0
	s_mov_b32 s8, 1
	s_mov_b64 s[20:21], 0
	v_mov_b32_e32 v0, 0
	s_branch .LBB0_1130

; __device__ __forceinline__ unsigned xb_ld(unsigned* p)              { return __hip_atomic_load(p, __ATOMIC_RELAXED, __HIP_MEMORY_SCOPE_AGENT); }
; __device__ __forceinline__ unsigned xb_add(unsigned* p, unsigned v) { return __hip_atomic_fetch_add(p, v, __ATOMIC_RELAXED, __HIP_MEMORY_SCOPE_AGENT); }
; #define XB_SPIN(cond, bar) do { unsigned _sp = 0; while (cond) { __builtin_amdgcn_s_sleep(1); \
;     if ((++_sp & 255u) == 0u) { if (xb_ld(&(bar)[XB_TMO])) break; if (_sp > XB_SPIN_CAP) { atomicAdd(&(bar)[XB_TMO], 1u); break; } } } } while (0)
; __device__ __forceinline__ void xcd_barrier(const XcdBarrier& b) {
;     ...
;             if (og + 1u == (tg + 1u) * nx) xb_add(&bar[XB_TOPGEN], 1u);
;             else XB_SPIN(xb_ld(&bar[XB_TOPGEN]) == tg, bar);
;             __builtin_amdgcn_fence(__ATOMIC_ACQUIRE, "agent");
;             xb_add(&bar[XB_XGEN(b.x)], 1u);
;             asm volatile("s_waitcnt vmcnt(0)" ::: "memory");
.LBB0_1157:
	s_or_b64 exec, exec, s[6:7]
	s_mov_b64 s[6:7], exec
	v_mbcnt_lo_u32_b32 v0, s6, 0
	v_mbcnt_hi_u32_b32 v0, s7, v0
	v_cmp_eq_u32_e32 vcc, 0, v0
	s_waitcnt vmcnt(0)
	s_nop 0
	s_and_saveexec_b64 s[14:15], vcc
	s_cbranch_execz .LBB0_1159
	s_bcnt1_i32_b64 s6, s[6:7]
	v_mov_b32_e32 v0, 0x2000
	v_mov_b32_e32 v1, s6
	global_atomic_add v0, v1, s[2:3] offset:1024

; __device__ __forceinline__ unsigned xb_ld(unsigned* p)              { return __hip_atomic_load(p, __ATOMIC_RELAXED, __HIP_MEMORY_SCOPE_AGENT); }
; __device__ __forceinline__ unsigned xb_add(unsigned* p, unsigned v) { return __hip_atomic_fetch_add(p, v, __ATOMIC_RELAXED, __HIP_MEMORY_SCOPE_AGENT); }
; #define XB_SPIN(cond, bar) do { unsigned _sp = 0; while (cond) { __builtin_amdgcn_s_sleep(1); \
;     if ((++_sp & 255u) == 0u) { if (xb_ld(&(bar)[XB_TMO])) break; if (_sp > XB_SPIN_CAP) { atomicAdd(&(bar)[XB_TMO], 1u); break; } } } } while (0)
; __device__ __forceinline__ void xcd_barrier(const XcdBarrier& b) {
;     ...
;         const unsigned old = xb_add(&bar[XB_XSUB(b.x)], 1u);
;         const unsigned gen = old / nloc;
;         if (old + 1u == (gen + 1u) * nloc) {
;             __builtin_amdgcn_fence(__ATOMIC_RELEASE, "agent");
;             asm volatile("s_waitcnt vmcnt(0)" ::: "memory");
;             const unsigned og = xb_add(&bar[XB_TOP], 1u);
;             const unsigned tg = og / nx;
;             if (og + 1u == (tg + 1u) * nx) xb_add(&bar[XB_TOPGEN], 1u);
;             else XB_SPIN(xb_ld(&bar[XB_TOPGEN]) == tg, bar);
;             __builtin_amdgcn_fence(__ATOMIC_ACQUIRE, "agent");
;             xb_add(&bar[XB_XGEN(b.x)], 1u);
;             asm volatile("s_waitcnt vmcnt(0)" ::: "memory");
;         } else {
;             XB_SPIN(xb_ld(&bar[XB_XGEN(b.x)]) == gen, bar);
.LBB0_1349:
	s_or_b64 exec, exec, s[12:13]
	v_cvt_f32_u32_e32 v4, v2
	s_waitcnt vmcnt(0)
	v_readfirstlane_b32 s6, v3
	v_sub_u32_e32 v3, 0, v2
	v_rcp_iflag_f32_e32 v4, v4
	v_add_u32_e32 v5, s6, v1
	v_mul_f32_e32 v4, 0x4f7ffffe, v4
	v_cvt_u32_f32_e32 v4, v4
	v_mul_lo_u32 v1, v3, v4
	v_mul_hi_u32 v1, v4, v1
	v_add_u32_e32 v1, v4, v1
	v_mul_hi_u32 v1, v5, v1
	v_mul_lo_u32 v3, v1, v2
	v_sub_u32_e32 v3, v5, v3
	v_add_u32_e32 v4, 1, v1
	v_cmp_ge_u32_e32 vcc, v3, v2
	s_nop 1
	v_cndmask_b32_e32 v1, v1, v4, vcc
	v_sub_u32_e32 v4, v3, v2
	v_cndmask_b32_e32 v3, v3, v4, vcc
	v_add_u32_e32 v4, 1, v1
	v_cmp_ge_u32_e32 vcc, v3, v2
	v_add_u32_e32 v3, 1, v5
	s_nop 0
	v_cndmask_b32_e32 v1, v1, v4, vcc
	v_mul_lo_u32 v4, v2, v1
	v_add_u32_e32 v2, v4, v2
	v_cmp_ne_u32_e32 vcc, v3, v2
	s_and_saveexec_b64 s[6:7], vcc
	s_xor_b64 s[6:7], exec, s[6:7]
	s_cbranch_execz .LBB0_1363
	s_waitcnt lgkmcnt(0)
	buffer_inv sc1
	v_mov_b32_e32 v0, 0x2000
	global_load_dword v0, v0, s[4:5] offset:1024 sc1
	s_add_u32 s16, s4, 0x2400
	s_addc_u32 s17, s5, 0
	s_waitcnt vmcnt(0)
	v_cmp_eq_u32_e32 vcc, v0, v1
	s_and_saveexec_b64 s[12:13], vcc
	s_cbranch_execz .LBB0_1362
	s_add_u32 s14, s72, 0x80200
	s_addc_u32 s15, s73, 0
	s_mov_b32 s8, 1
	s_mov_b64 s[18:19], 0
	v_mov_b32_e32 v0, 0
	s_branch .LBB0_1353
